# combined edits, out-proj epilogue gate vectors read from LDS in all four passes
# speedup vs baseline: 1.0161x; 1.0066x over previous
; #define MFMA32(a, b, c) __builtin_amdgcn_mfma_f32_32x32x16_bf16((a), (b), (c), 0, 0, 0)
; template <int EPI>
; DI void gemm_phase(const Params& p, char* lds, const bfu* __restrict__ A, const bfu* __restrict__ BT, int ntn, int l, const float* xin) {
;     ...
;       for (int s = 0; s < 4; ++s) {
;         if (s < 3) {
;           const unsigned co = (unsigned)((((s + 1) * 2 + h) ^ swz) << 4);
;           af[(s + 1) & 1][0] = *(const bf16x8*)(pa + co); af[(s + 1) & 1][1] = *(const bf16x8*)(pa + 4096 + co);
; #pragma unroll
;           for (int j = 0; j < 4; ++j) bfr[(s + 1) & 1][j] = *(const bf16x8*)(pb + j * 4096 + co);
;         }
;         SBAR();
; #pragma unroll
;         for (int i = 0; i < 2; ++i)
; #pragma unroll
;           for (int j = 0; j < 4; ++j) {
;             acc[i][j] = MFMA32(bfr[s & 1][j], af[s & 1][i], acc[i][j]);
;             if (s < 2 && (j & 1) && dnext) DMA_PIECE(dA, dB, dk, dso, s * 4 + i * 2 + (j >> 1));
;           }
;         SBAR();
;     ...
;       char* stg = lds + 65536 + wave * 8704;
;       const float* gate = (const float*)(p.ws + WS_MOD) + l * 6144 + (m0 >> 14) * 3072 + 2048;
;       float4 xn[8];
;     ...
;       LOADX(0);
; #pragma unroll
;       for (int ps = 0; ps < 4; ++ps) {
;         const int i = ps >> 1, jp = ps & 1;
;         float4 xc[8];
; #pragma unroll
;         for (int it = 0; it < 8; ++it) xc[it] = xn[it];
;         if (ps + 1 < 4) LOADX(ps + 1);
;         if (ps) WSYNC();
; #pragma unroll
;         for (int j2 = 0; j2 < 2; ++j2)
; #pragma unroll
;           for (int g = 0; g < 4; ++g) {
;             const f32x16& a = acc[i][2 * jp + j2];
;             float4 o; o.x = a[4 * g]; o.y = a[4 * g + 1]; o.z = a[4 * g + 2]; o.w = a[4 * g + 3];
;             *(float4*)(stg + r * 272 + (j2 * 32 + 8 * g + 4 * h) * 4) = o;
;           }
;         WSYNC();
; #pragma unroll
;         for (int it = 0; it < 8; ++it) {
;           const int id = it * 64 + lane, row = id >> 4, c = id & 15;
;           const float4 y = *(const float4*)(stg + row * 272 + c * 16);
;           const int m = m0 + wm * 64 + i * 32 + row, n = n0 + wn * 128 + jp * 64 + c * 4;
;           const float4 xv = xc[it];
;           const float4 gv = *(const float4*)(gate + n);
;           float4 o; o.x = xv.x + gv.x * y.x; o.y = xv.y + gv.y * y.y; o.z = xv.z + gv.z * y.z; o.w = xv.w + gv.w * y.w;
;           *(float4*)(p.out + (size_t)m * 1024 + n) = o;
.LBB0_801:
	v_add_u32_e32 v132, v209, v200
	v_add_u32_e32 v148, v210, v200
	ds_read_b128 v[128:131], v132
	ds_read_b128 v[132:135], v132 offset:4096
	ds_read_b128 v[136:139], v148 offset:32768
	ds_read_b128 v[140:143], v148 offset:36864
	ds_read_b128 v[144:147], v148 offset:40960
	ds_read_b128 v[148:151], v148 offset:45056
	s_waitcnt lgkmcnt(9)
	v_mfma_f32_32x32x16_bf16 v[112:127], v[172:175], v[164:167], v[112:127]
	s_waitcnt lgkmcnt(8)
	v_mfma_f32_32x32x16_bf16 v[96:111], v[168:171], v[164:167], v[96:111]
	s_waitcnt lgkmcnt(7)
	v_mfma_f32_32x32x16_bf16 v[80:95], v[160:163], v[164:167], v[80:95]
	s_waitcnt lgkmcnt(6)
	v_mfma_f32_32x32x16_bf16 v[64:79], v[156:159], v[164:167], v[64:79]
	v_mfma_f32_32x32x16_bf16 v[48:63], v[172:175], v[152:155], v[48:63]
	v_mfma_f32_32x32x16_bf16 v[32:47], v[168:171], v[152:155], v[32:47]
	v_mfma_f32_32x32x16_bf16 v[16:31], v[160:163], v[152:155], v[16:31]
	v_mfma_f32_32x32x16_bf16 v[0:15], v[156:159], v[152:155], v[0:15]
	s_waitcnt lgkmcnt(3)
	v_mfma_f32_32x32x16_bf16 v[112:127], v[136:139], v[128:131], v[112:127]
	s_waitcnt lgkmcnt(2)
	v_mfma_f32_32x32x16_bf16 v[96:111], v[140:143], v[128:131], v[96:111]
	s_waitcnt lgkmcnt(1)
	v_mfma_f32_32x32x16_bf16 v[80:95], v[144:147], v[128:131], v[80:95]
	s_waitcnt lgkmcnt(0)
	v_mfma_f32_32x32x16_bf16 v[64:79], v[148:151], v[128:131], v[64:79]
	v_mfma_f32_32x32x16_bf16 v[48:63], v[136:139], v[132:135], v[48:63]
	v_mfma_f32_32x32x16_bf16 v[32:47], v[140:143], v[132:135], v[32:47]
	v_mfma_f32_32x32x16_bf16 v[16:31], v[144:147], v[132:135], v[16:31]
	v_mfma_f32_32x32x16_bf16 v[0:15], v[148:151], v[132:135], v[0:15]
	s_lshr_b32 s4, s35, 6
	s_mulk_i32 s4, 0xc00
	s_ashr_i32 s5, s4, 31
	s_lshl_b64 s[4:5], s[4:5], 2
	s_add_u32 s4, s49, s4
	s_addc_u32 s5, s50, s5
	s_add_i32 s10, s10, s51
	v_or_b32_e32 v128, s10, v201
	v_ashrrev_i32_e32 v129, 31, v128
	v_lshlrev_b64 v[162:163], 12, v[128:129]
	v_or_b32_e32 v128, s10, v202
	v_ashrrev_i32_e32 v129, 31, v128
	v_lshlrev_b64 v[174:175], 12, v[128:129]
	v_or_b32_e32 v128, s10, v203
	v_ashrrev_i32_e32 v129, 31, v128
	v_lshlrev_b64 v[188:189], 12, v[128:129]
	v_or_b32_e32 v128, s10, v204
	v_or_b32_e32 v134, s10, v207
	v_ashrrev_i32_e32 v129, 31, v128
	v_ashrrev_i32_e32 v135, 31, v134
	v_lshlrev_b64 v[150:151], 12, v[128:129]
	v_or_b32_e32 v128, s10, v205
	v_or_b32_e32 v130, s10, v206
	v_lshlrev_b64 v[140:141], 12, v[134:135]
	v_or_b32_e32 v134, s10, v208
	s_waitcnt vmcnt(0) lgkmcnt(0)
	s_barrier
	v_ashrrev_i32_e32 v129, 31, v128
	v_ashrrev_i32_e32 v131, 31, v130
	v_ashrrev_i32_e32 v135, 31, v134
	ds_write_b128 v211, v[112:115]
	ds_write_b128 v211, v[116:119] offset:32
	ds_write_b128 v211, v[120:123] offset:64
	ds_write_b128 v211, v[124:127] offset:96
	ds_write_b128 v211, v[96:99] offset:128
	ds_write_b128 v211, v[100:103] offset:160
	ds_write_b128 v211, v[104:107] offset:192
	ds_write_b128 v211, v[108:111] offset:224
	v_or_b32_e32 v100, s8, v192
	v_lshl_add_u64 v[132:133], s[8:9], 2, v[178:179]
	v_lshlrev_b64 v[148:149], 12, v[128:129]
	v_lshlrev_b64 v[142:143], 12, v[130:131]
	v_lshlrev_b64 v[134:135], 12, v[134:135]
	s_add_u32 s4, s4, 0x26c2000
	v_ashrrev_i32_e32 v101, 31, v100
	v_lshl_add_u64 v[152:153], v[132:133], 0, v[174:175]
	v_lshl_add_u64 v[144:145], v[132:133], 0, v[188:189]
	v_lshl_add_u64 v[136:137], v[132:133], 0, v[150:151]
	v_lshl_add_u64 v[128:129], v[132:133], 0, v[148:149]
	v_lshl_add_u64 v[130:131], v[132:133], 0, v[142:143]
	v_lshl_add_u64 v[138:139], v[132:133], 0, v[140:141]
	v_lshl_add_u64 v[146:147], v[132:133], 0, v[134:135]
	s_addc_u32 s5, s5, 0
	v_lshlrev_b64 v[102:103], 2, v[100:101]
	v_lshl_add_u64 v[164:165], v[132:133], 0, v[162:163]
	v_lshl_add_u64 v[160:161], s[4:5], 0, v[102:103]
	global_load_dwordx4 v[96:99], v[146:147], off offset:256
	global_load_dwordx4 v[108:111], v[146:147], off
	global_load_dwordx4 v[104:107], v[138:139], off offset:256
	global_load_dwordx4 v[116:119], v[138:139], off
	global_load_dwordx4 v[112:115], v[130:131], off offset:256
	global_load_dwordx4 v[124:127], v[130:131], off
	global_load_dwordx4 v[120:123], v[128:129], off offset:256
	global_load_dwordx4 v[156:159], v[128:129], off
	s_nop 0
	global_load_dwordx4 v[128:131], v[136:137], off offset:256
	global_load_dwordx4 v[166:169], v[136:137], off
	s_nop 0
	global_load_dwordx4 v[136:139], v[144:145], off offset:256
	global_load_dwordx4 v[170:173], v[144:145], off
	s_nop 0
	global_load_dwordx4 v[144:147], v[152:153], off offset:256
	global_load_dwordx4 v[184:187], v[152:153], off
	s_nop 0
	global_load_dwordx4 v[152:155], v[164:165], off offset:256
	global_load_dwordx4 v[214:217], v[164:165], off
	s_waitcnt lgkmcnt(0)
	global_load_dwordx4 v[218:221], v[160:161], off
	v_lshlrev_b32_e32 v246, 5, v199
	v_add_u32_e32 v246, 0x22080, v246
	ds_read_b128 v[222:225], v212
	ds_read_b128 v[226:229], v212 offset:1088
	v_lshl_add_u64 v[164:165], s[28:29], 0, v[102:103]
	v_lshl_add_u64 v[230:231], v[164:165], 0, v[162:163]
	s_or_b32 s8, s10, 32
	v_or_b32_e32 v100, 64, v100
	v_or_b32_e32 v102, s8, v201
	v_ashrrev_i32_e32 v101, 31, v100
	v_ashrrev_i32_e32 v103, 31, v102
	v_lshl_add_u64 v[162:163], v[100:101], 2, s[4:5]
	v_readlane_b32 s4, v255, 10
	s_add_i32 s66, s66, s4
	s_and_b64 vcc, exec, s[6:7]
	s_waitcnt vmcnt(0) lgkmcnt(1)
	ds_write_b128 v246, v[218:221]
	v_pk_fma_f32 v[214:215], v[222:223], v[218:219], v[214:215]
	v_pk_fma_f32 v[216:217], v[224:225], v[220:221], v[216:217]
	global_store_dwordx4 v[230:231], v[214:217], off nt
	s_nop 0
	ds_read_b128 v[214:217], v246
	v_lshl_add_u64 v[222:223], v[164:165], 0, v[174:175]
	v_lshl_add_u64 v[224:225], v[164:165], 0, v[188:189]
	v_lshlrev_b64 v[188:189], 12, v[102:103]
	ds_read_b128 v[218:221], v212 offset:3264
	s_waitcnt lgkmcnt(1)
; #define WSYNC() asm volatile("s_waitcnt lgkmcnt(0)" ::: "memory")
; #define LOADX(ps_) do { _Pragma("unroll") for (int it = 0; it < 8; ++it) { const int id = it * 64 + lane, row = id >> 4, c = id & 15; \
;           xn[it] = *(const float4*)(xin + (size_t)(m0 + wm * 64 + ((ps_) >> 1) * 32 + row) * 1024 + n0 + wn * 128 + ((ps_) & 1) * 64 + c * 4); } } while (0)
; template <int EPI>
; DI void gemm_phase(const Params& p, char* lds, const bfu* __restrict__ A, const bfu* __restrict__ BT, int ntn, int l, const float* xin) {
;     ...
;       for (int ps = 0; ps < 4; ++ps) {
;         const int i = ps >> 1, jp = ps & 1;
;         float4 xc[8];
; #pragma unroll
;         for (int it = 0; it < 8; ++it) xc[it] = xn[it];
;         if (ps + 1 < 4) LOADX(ps + 1);
;         if (ps) WSYNC();
; #pragma unroll
;         for (int j2 = 0; j2 < 2; ++j2)
; #pragma unroll
;           for (int g = 0; g < 4; ++g) {
;             const f32x16& a = acc[i][2 * jp + j2];
;             float4 o; o.x = a[4 * g]; o.y = a[4 * g + 1]; o.z = a[4 * g + 2]; o.w = a[4 * g + 3];
;             *(float4*)(stg + r * 272 + (j2 * 32 + 8 * g + 4 * h) * 4) = o;
;           }
;         WSYNC();
; #pragma unroll
;         for (int it = 0; it < 8; ++it) {
;           const int id = it * 64 + lane, row = id >> 4, c = id & 15;
;           const float4 y = *(const float4*)(stg + row * 272 + c * 16);
;           const int m = m0 + wm * 64 + i * 32 + row, n = n0 + wn * 128 + jp * 64 + c * 4;
;           const float4 xv = xc[it];
;           const float4 gv = *(const float4*)(gate + n);
;           float4 o; o.x = xv.x + gv.x * y.x; o.y = xv.y + gv.y * y.y; o.z = xv.z + gv.z * y.z; o.w = xv.w + gv.w * y.w;
;           *(float4*)(p.out + (size_t)m * 1024 + n) = o;
;         }
	v_pk_fma_f32 v[184:185], v[226:227], v[214:215], v[184:185]
	v_pk_fma_f32 v[186:187], v[228:229], v[216:217], v[186:187]
	global_store_dwordx4 v[222:223], v[184:187], off nt
	s_nop 0
	ds_read_b128 v[184:187], v246
	ds_read_b128 v[214:217], v212 offset:2176
	v_lshl_add_u64 v[226:227], v[164:165], 0, v[134:135]
	v_lshl_add_u64 v[228:229], v[132:133], 0, v[188:189]
	s_waitcnt lgkmcnt(0)
	v_pk_fma_f32 v[170:171], v[214:215], v[184:185], v[170:171]
	v_pk_fma_f32 v[172:173], v[216:217], v[186:187], v[172:173]
	global_store_dwordx4 v[224:225], v[170:173], off nt
	s_nop 0
	ds_read_b128 v[170:173], v246
	v_lshl_add_u64 v[214:215], v[164:165], 0, v[150:151]
	v_lshl_add_u64 v[216:217], v[164:165], 0, v[148:149]
	ds_read_b128 v[148:151], v212 offset:5440
	s_waitcnt lgkmcnt(1)
	v_pk_fma_f32 v[166:167], v[218:219], v[170:171], v[166:167]
	v_pk_fma_f32 v[168:169], v[220:221], v[172:173], v[168:169]
	global_store_dwordx4 v[214:215], v[166:169], off nt
	s_nop 0
	ds_read_b128 v[166:169], v246
	ds_read_b128 v[170:173], v212 offset:4352
	v_lshl_add_u64 v[218:219], v[164:165], 0, v[142:143]
	v_lshl_add_u64 v[220:221], v[164:165], 0, v[140:141]
	ds_read_b128 v[140:143], v212 offset:7616
	s_waitcnt lgkmcnt(1)
	v_pk_fma_f32 v[156:157], v[170:171], v[166:167], v[156:157]
	v_pk_fma_f32 v[158:159], v[172:173], v[168:169], v[158:159]
	global_store_dwordx4 v[216:217], v[156:159], off nt
	s_nop 0
	ds_read_b128 v[156:159], v246
	v_or_b32_e32 v166, s8, v208
	v_ashrrev_i32_e32 v167, 31, v166
	v_lshlrev_b64 v[166:167], 12, v[166:167]
	v_lshl_add_u64 v[236:237], v[132:133], 0, v[166:167]
	s_waitcnt lgkmcnt(0)
	v_pk_fma_f32 v[124:125], v[148:149], v[156:157], v[124:125]
	v_pk_fma_f32 v[126:127], v[150:151], v[158:159], v[126:127]
	global_store_dwordx4 v[218:219], v[124:127], off nt
	s_nop 0
	ds_read_b128 v[124:127], v246
	ds_read_b128 v[148:151], v212 offset:6528
	v_or_b32_e32 v156, s8, v206
	v_or_b32_e32 v158, s8, v207
	v_ashrrev_i32_e32 v157, 31, v156
	v_ashrrev_i32_e32 v159, 31, v158
	v_lshlrev_b64 v[170:171], 12, v[156:157]
	v_lshlrev_b64 v[168:169], 12, v[158:159]
	v_lshl_add_u64 v[250:251], v[132:133], 0, v[170:171]
	v_lshl_add_u64 v[252:253], v[132:133], 0, v[168:169]
	s_waitcnt lgkmcnt(0)
	v_pk_fma_f32 v[116:117], v[148:149], v[124:125], v[116:117]
	v_pk_fma_f32 v[118:119], v[150:151], v[126:127], v[118:119]
	global_store_dwordx4 v[220:221], v[116:119], off nt
	s_nop 0
	ds_read_b128 v[116:119], v246
	v_or_b32_e32 v124, s8, v202
	v_or_b32_e32 v126, s8, v203
	v_or_b32_e32 v148, s8, v204
	v_or_b32_e32 v150, s8, v205
	v_ashrrev_i32_e32 v125, 31, v124
	v_ashrrev_i32_e32 v127, 31, v126
	v_ashrrev_i32_e32 v149, 31, v148
	v_ashrrev_i32_e32 v151, 31, v150
	v_lshlrev_b64 v[186:187], 12, v[124:125]
	v_lshlrev_b64 v[184:185], 12, v[126:127]
	v_lshlrev_b64 v[174:175], 12, v[148:149]
	v_lshlrev_b64 v[172:173], 12, v[150:151]
	v_lshl_add_u64 v[232:233], v[132:133], 0, v[186:187]
	v_lshl_add_u64 v[240:241], v[132:133], 0, v[184:185]
	v_lshl_add_u64 v[242:243], v[132:133], 0, v[174:175]
	v_lshl_add_u64 v[248:249], v[132:133], 0, v[172:173]
	s_waitcnt lgkmcnt(0)
	v_pk_fma_f32 v[100:101], v[140:141], v[116:117], v[108:109]
	v_pk_fma_f32 v[102:103], v[142:143], v[118:119], v[110:111]
	global_store_dwordx4 v[226:227], v[100:103], off nt
	global_load_dwordx4 v[100:103], v[236:237], off
	s_nop 0
	global_load_dwordx4 v[108:111], v[252:253], off
	global_load_dwordx4 v[116:119], v[250:251], off
	global_load_dwordx4 v[124:127], v[248:249], off
	global_load_dwordx4 v[132:135], v[242:243], off
	global_load_dwordx4 v[140:143], v[240:241], off
	global_load_dwordx4 v[148:151], v[232:233], off
	global_load_dwordx4 v[156:159], v[228:229], off
	s_waitcnt lgkmcnt(0)
	ds_write_b128 v211, v[80:83]
	ds_write_b128 v211, v[84:87] offset:32
	ds_write_b128 v211, v[88:91] offset:64
	ds_write_b128 v211, v[92:95] offset:96
	ds_write_b128 v211, v[64:67] offset:128
	ds_write_b128 v211, v[68:71] offset:160
	ds_write_b128 v211, v[72:75] offset:192
	ds_write_b128 v211, v[76:79] offset:224
	s_waitcnt lgkmcnt(0)
	global_load_dwordx4 v[64:67], v[162:163], off
	ds_read_b128 v[68:71], v212
	ds_read_b128 v[72:75], v212 offset:1088
	s_waitcnt vmcnt(0) lgkmcnt(1)
	ds_write_b128 v246, v[64:67] offset:16
	v_pk_fma_f32 v[64:65], v[68:69], v[64:65], v[152:153]
	v_pk_fma_f32 v[66:67], v[70:71], v[66:67], v[154:155]
	global_store_dwordx4 v[230:231], v[64:67], off offset:256 nt
	s_nop 0
	ds_read_b128 v[64:67], v246 offset:16
	s_waitcnt lgkmcnt(0)
	v_pk_fma_f32 v[64:65], v[72:73], v[64:65], v[144:145]
	v_pk_fma_f32 v[66:67], v[74:75], v[66:67], v[146:147]
	global_store_dwordx4 v[222:223], v[64:67], off offset:256 nt
	s_nop 0
	ds_read_b128 v[64:67], v246 offset:16
	ds_read_b128 v[68:71], v212 offset:2176
	ds_read_b128 v[72:75], v212 offset:3264
	s_waitcnt lgkmcnt(1)
	v_pk_fma_f32 v[64:65], v[68:69], v[64:65], v[136:137]
	v_pk_fma_f32 v[66:67], v[70:71], v[66:67], v[138:139]
	global_store_dwordx4 v[224:225], v[64:67], off offset:256 nt
	s_nop 0
	ds_read_b128 v[64:67], v246 offset:16
	s_waitcnt lgkmcnt(0)
	v_pk_fma_f32 v[64:65], v[72:73], v[64:65], v[128:129]
	v_pk_fma_f32 v[66:67], v[74:75], v[66:67], v[130:131]
	global_store_dwordx4 v[214:215], v[64:67], off offset:256 nt
	s_nop 0
	ds_read_b128 v[64:67], v246 offset:16
	ds_read_b128 v[68:71], v212 offset:4352
	ds_read_b128 v[72:75], v212 offset:5440
	s_waitcnt lgkmcnt(1)
	v_pk_fma_f32 v[64:65], v[68:69], v[64:65], v[120:121]
	v_pk_fma_f32 v[66:67], v[70:71], v[66:67], v[122:123]
	global_store_dwordx4 v[216:217], v[64:67], off offset:256 nt
	s_nop 0
	ds_read_b128 v[64:67], v246 offset:16
	s_waitcnt lgkmcnt(0)
; #define WSYNC() asm volatile("s_waitcnt lgkmcnt(0)" ::: "memory")
; #define LOADX(ps_) do { _Pragma("unroll") for (int it = 0; it < 8; ++it) { const int id = it * 64 + lane, row = id >> 4, c = id & 15; \
;           xn[it] = *(const float4*)(xin + (size_t)(m0 + wm * 64 + ((ps_) >> 1) * 32 + row) * 1024 + n0 + wn * 128 + ((ps_) & 1) * 64 + c * 4); } } while (0)
; template <int EPI>
; DI void gemm_phase(const Params& p, char* lds, const bfu* __restrict__ A, const bfu* __restrict__ BT, int ntn, int l, const float* xin) {
;     ...
;       for (int ps = 0; ps < 4; ++ps) {
;         const int i = ps >> 1, jp = ps & 1;
;         float4 xc[8];
; #pragma unroll
;         for (int it = 0; it < 8; ++it) xc[it] = xn[it];
;         if (ps + 1 < 4) LOADX(ps + 1);
;         if (ps) WSYNC();
; #pragma unroll
;         for (int j2 = 0; j2 < 2; ++j2)
; #pragma unroll
;           for (int g = 0; g < 4; ++g) {
;             const f32x16& a = acc[i][2 * jp + j2];
;             float4 o; o.x = a[4 * g]; o.y = a[4 * g + 1]; o.z = a[4 * g + 2]; o.w = a[4 * g + 3];
;             *(float4*)(stg + r * 272 + (j2 * 32 + 8 * g + 4 * h) * 4) = o;
;           }
;         WSYNC();
; #pragma unroll
;         for (int it = 0; it < 8; ++it) {
;           const int id = it * 64 + lane, row = id >> 4, c = id & 15;
;           const float4 y = *(const float4*)(stg + row * 272 + c * 16);
;           const int m = m0 + wm * 64 + i * 32 + row, n = n0 + wn * 128 + jp * 64 + c * 4;
;           const float4 xv = xc[it];
;           const float4 gv = *(const float4*)(gate + n);
;           float4 o; o.x = xv.x + gv.x * y.x; o.y = xv.y + gv.y * y.y; o.z = xv.z + gv.z * y.z; o.w = xv.w + gv.w * y.w;
;           *(float4*)(p.out + (size_t)m * 1024 + n) = o;
;         }
	v_pk_fma_f32 v[64:65], v[72:73], v[64:65], v[112:113]
	v_pk_fma_f32 v[66:67], v[74:75], v[66:67], v[114:115]
	global_store_dwordx4 v[218:219], v[64:67], off offset:256 nt
	s_nop 0
	ds_read_b128 v[64:67], v246 offset:16
	ds_read_b128 v[68:71], v212 offset:6528
	ds_read_b128 v[72:75], v212 offset:7616
	s_waitcnt lgkmcnt(1)
	v_pk_fma_f32 v[64:65], v[68:69], v[64:65], v[104:105]
	v_pk_fma_f32 v[66:67], v[70:71], v[66:67], v[106:107]
	global_store_dwordx4 v[220:221], v[64:67], off offset:256 nt
	s_nop 0
	ds_read_b128 v[64:67], v246 offset:16
	s_waitcnt lgkmcnt(0)
	v_pk_fma_f32 v[64:65], v[72:73], v[64:65], v[96:97]
	v_pk_fma_f32 v[66:67], v[74:75], v[66:67], v[98:99]
	global_store_dwordx4 v[226:227], v[64:67], off offset:256 nt
	global_load_dwordx4 v[64:67], v[236:237], off offset:256
	s_nop 0
	global_load_dwordx4 v[68:71], v[252:253], off offset:256
	global_load_dwordx4 v[72:75], v[250:251], off offset:256
	global_load_dwordx4 v[76:79], v[248:249], off offset:256
	global_load_dwordx4 v[80:83], v[242:243], off offset:256
	global_load_dwordx4 v[84:87], v[240:241], off offset:256
	global_load_dwordx4 v[88:91], v[232:233], off offset:256
	global_load_dwordx4 v[92:95], v[228:229], off offset:256
	s_waitcnt lgkmcnt(0)
	ds_write_b128 v211, v[48:51]
	ds_write_b128 v211, v[52:55] offset:32
	ds_write_b128 v211, v[56:59] offset:64
	ds_write_b128 v211, v[60:63] offset:96
	ds_write_b128 v211, v[32:35] offset:128
	ds_write_b128 v211, v[36:39] offset:160
	ds_write_b128 v211, v[40:43] offset:192
	ds_write_b128 v211, v[44:47] offset:224
	s_waitcnt lgkmcnt(0)
	s_nop 0
	ds_read_b128 v[32:35], v246
	ds_read_b128 v[36:39], v212
	ds_read_b128 v[40:43], v212 offset:1088
	v_lshl_add_u64 v[44:45], v[164:165], 0, v[188:189]
	v_lshl_add_u64 v[46:47], v[164:165], 0, v[186:187]
	v_lshl_add_u64 v[48:49], v[164:165], 0, v[184:185]
	v_lshl_add_u64 v[50:51], v[164:165], 0, v[174:175]
	v_lshl_add_u64 v[52:53], v[164:165], 0, v[172:173]
	v_lshl_add_u64 v[54:55], v[164:165], 0, v[170:171]
	v_lshl_add_u64 v[56:57], v[164:165], 0, v[168:169]
	s_waitcnt vmcnt(0) lgkmcnt(1)
	v_pk_fma_f32 v[32:33], v[36:37], v[32:33], v[156:157]
	v_pk_fma_f32 v[34:35], v[38:39], v[34:35], v[158:159]
	global_store_dwordx4 v[44:45], v[32:35], off nt
	s_nop 0
	ds_read_b128 v[32:35], v246
	ds_read_b128 v[36:39], v212 offset:2176
	s_waitcnt lgkmcnt(1)
	v_pk_fma_f32 v[32:33], v[40:41], v[32:33], v[148:149]
	v_pk_fma_f32 v[34:35], v[42:43], v[34:35], v[150:151]
	global_store_dwordx4 v[46:47], v[32:35], off nt
	s_nop 0
	ds_read_b128 v[32:35], v246
	ds_read_b128 v[40:43], v212 offset:3264
	s_waitcnt lgkmcnt(1)
	v_pk_fma_f32 v[32:33], v[36:37], v[32:33], v[140:141]
	v_pk_fma_f32 v[34:35], v[38:39], v[34:35], v[142:143]
	global_store_dwordx4 v[48:49], v[32:35], off nt
	s_nop 0
	ds_read_b128 v[32:35], v246
	ds_read_b128 v[36:39], v212 offset:4352
	s_waitcnt lgkmcnt(1)
	v_pk_fma_f32 v[32:33], v[40:41], v[32:33], v[132:133]
	v_pk_fma_f32 v[34:35], v[42:43], v[34:35], v[134:135]
	global_store_dwordx4 v[50:51], v[32:35], off nt
	s_nop 0
	ds_read_b128 v[32:35], v246
	ds_read_b128 v[40:43], v212 offset:5440
	s_waitcnt lgkmcnt(1)
	v_pk_fma_f32 v[32:33], v[36:37], v[32:33], v[124:125]
	v_pk_fma_f32 v[34:35], v[38:39], v[34:35], v[126:127]
	global_store_dwordx4 v[52:53], v[32:35], off nt
	s_nop 0
	ds_read_b128 v[32:35], v246
	ds_read_b128 v[36:39], v212 offset:6528
	s_waitcnt lgkmcnt(1)
	v_pk_fma_f32 v[32:33], v[40:41], v[32:33], v[116:117]
	v_pk_fma_f32 v[34:35], v[42:43], v[34:35], v[118:119]
	global_store_dwordx4 v[54:55], v[32:35], off nt
	s_nop 0
	ds_read_b128 v[32:35], v246
	ds_read_b128 v[40:43], v212 offset:7616
	s_waitcnt lgkmcnt(1)
	v_pk_fma_f32 v[32:33], v[36:37], v[32:33], v[108:109]
	v_pk_fma_f32 v[34:35], v[38:39], v[34:35], v[110:111]
	global_store_dwordx4 v[56:57], v[32:35], off nt
	s_nop 0
	ds_read_b128 v[32:35], v246
	v_lshl_add_u64 v[36:37], v[164:165], 0, v[166:167]
	s_waitcnt lgkmcnt(0)
	v_pk_fma_f32 v[32:33], v[40:41], v[32:33], v[100:101]
	v_pk_fma_f32 v[34:35], v[42:43], v[34:35], v[102:103]
	global_store_dwordx4 v[36:37], v[32:35], off nt
	s_waitcnt lgkmcnt(0)
	ds_write_b128 v211, v[16:19]
	ds_write_b128 v211, v[20:23] offset:32
	ds_write_b128 v211, v[24:27] offset:64
	ds_write_b128 v211, v[28:31] offset:96
	ds_write_b128 v211, v[0:3] offset:128
	ds_write_b128 v211, v[4:7] offset:160
	ds_write_b128 v211, v[8:11] offset:192
	ds_write_b128 v211, v[12:15] offset:224
	s_waitcnt lgkmcnt(0)
	s_nop 0
	ds_read_b128 v[0:3], v246 offset:16
	ds_read_b128 v[4:7], v212
	ds_read_b128 v[8:11], v212 offset:1088
	s_waitcnt vmcnt(0) lgkmcnt(1)
	v_pk_fma_f32 v[0:1], v[4:5], v[0:1], v[92:93]
	v_pk_fma_f32 v[2:3], v[6:7], v[2:3], v[94:95]
	global_store_dwordx4 v[44:45], v[0:3], off offset:256 nt
	s_nop 0
	ds_read_b128 v[0:3], v246 offset:16
	s_waitcnt lgkmcnt(0)
	v_pk_fma_f32 v[0:1], v[8:9], v[0:1], v[88:89]
	v_pk_fma_f32 v[2:3], v[10:11], v[2:3], v[90:91]
	global_store_dwordx4 v[46:47], v[0:3], off offset:256 nt
	s_nop 0
	ds_read_b128 v[0:3], v246 offset:16
	ds_read_b128 v[4:7], v212 offset:2176
	ds_read_b128 v[8:11], v212 offset:3264
	s_waitcnt lgkmcnt(1)
	v_pk_fma_f32 v[0:1], v[4:5], v[0:1], v[84:85]
	v_pk_fma_f32 v[2:3], v[6:7], v[2:3], v[86:87]
	global_store_dwordx4 v[48:49], v[0:3], off offset:256 nt
	s_nop 0
	ds_read_b128 v[0:3], v246 offset:16
	s_waitcnt lgkmcnt(0)
	v_pk_fma_f32 v[0:1], v[8:9], v[0:1], v[80:81]
	v_pk_fma_f32 v[2:3], v[10:11], v[2:3], v[82:83]
	global_store_dwordx4 v[50:51], v[0:3], off offset:256 nt
	s_nop 0
	ds_read_b128 v[0:3], v246 offset:16
	ds_read_b128 v[4:7], v212 offset:4352
	ds_read_b128 v[8:11], v212 offset:5440
	s_waitcnt lgkmcnt(1)
	v_pk_fma_f32 v[0:1], v[4:5], v[0:1], v[76:77]
	v_pk_fma_f32 v[2:3], v[6:7], v[2:3], v[78:79]
	global_store_dwordx4 v[52:53], v[0:3], off offset:256 nt
	s_nop 0
	ds_read_b128 v[0:3], v246 offset:16
	s_waitcnt lgkmcnt(0)
	v_pk_fma_f32 v[0:1], v[8:9], v[0:1], v[72:73]
	v_pk_fma_f32 v[2:3], v[10:11], v[2:3], v[74:75]
	global_store_dwordx4 v[54:55], v[0:3], off offset:256 nt
	s_nop 0
	ds_read_b128 v[0:3], v246 offset:16
	ds_read_b128 v[4:7], v212 offset:6528
	ds_read_b128 v[8:11], v212 offset:7616
	s_waitcnt lgkmcnt(1)
	v_pk_fma_f32 v[0:1], v[4:5], v[0:1], v[68:69]
	v_pk_fma_f32 v[2:3], v[6:7], v[2:3], v[70:71]
	global_store_dwordx4 v[56:57], v[0:3], off offset:256 nt
	s_nop 0
	ds_read_b128 v[0:3], v246 offset:16
	s_waitcnt lgkmcnt(0)
	v_pk_fma_f32 v[0:1], v[8:9], v[0:1], v[64:65]
	v_pk_fma_f32 v[2:3], v[10:11], v[2:3], v[66:67]
	global_store_dwordx4 v[36:37], v[0:3], off offset:256 nt
	s_cbranch_vccnz .LBB0_822
